# SSM Y phase (64-row items): segment-chain pair loads issued together, same recurrence order; ssm_sgemm item: weight fragments in flight across first barrier
# speedup vs baseline: 1.0050x; 1.0050x over previous
; #define LAS __attribute__((address_space(3)))
; __device__ __forceinline__ void ssm_sgemm_item(Frame& F, const Args& AR, int l, int item) {
;     constexpr int K = 256, LDA = K * 2 + 16, MT = 4, NROW = 64, SL_OFF = 36864, SLD = 260, EX_OFF = 104448;
;     const int g = item & 31, rt = item >> 5, row0 = rt * 64;
;     const bf16* P = (const bf16*)(F.ws + WS_P);
;     LAS unsigned char* at = F.lds;
;     LAS float* sl = (LAS float*)(F.lds + SL_OFF); LAS float* ex = (LAS float*)(F.lds + EX_OFF);
;     const bf16* Bt = (const bf16*)(F.ws + WS_SSMWS) + (size_t)(l * 32 + g) * 256 * 256 + (size_t)(F.wave * 32) * K;
;     bf16x8v b0[8][2];
;     wave_bfrags<K>(Bt, 0, b0, F.lane);
;     __syncthreads();
;     for (int idx = F.tid; idx < NROW * 32; idx += NTHR) { const int piece = idx & 1, tok = (idx >> 1) & 15, row = idx >> 5, cr = row0 + row;
;         v4u v = {0u, 0u, 0u, 0u}; if (cr < NCR) v = *(const v4u*)(P + (size_t)(cr * 16 + tok) * DIN + SSM_OFF + g * 16 + piece * 8);
;         *(LAS v4u*)(at + row * LDA + (tok * 16 + piece * 8) * 2) = v; }
.LBB0_1270:
	v_mov_b32_e32 v70, v0
	s_mov_b64 s[0:1], -1
	v_readfirstlane_b32 s11, v70
	s_ashr_i32 s12, s11, 6
	v_and_b32_e32 v149, 63, v70
	s_cmpk_gt_i32 s10, 0x10f
	s_cbranch_scc0 .LBB0_1276
	s_cmpk_gt_u32 s10, 0x117
	s_cbranch_scc0 .LBB0_1445
	s_cmpk_gt_u32 s10, 0x197
	s_cbranch_scc0 .LBB0_1370
	s_cmpk_gt_u32 s10, 0x3b7
	s_cbranch_scc0 .LBB0_1349
	s_add_i32 s8, s10, 0xfffffc48
	s_and_b32 s14, s8, 31
	s_lshr_b32 s13, s8, 5
	s_lshl_b32 s0, s14, 17
	v_readlane_b32 s1, v254, 49
	s_lshl_b32 s15, s13, 6
	s_or_b32 s0, s0, s1
	v_readlane_b32 s1, v253, 1
	s_add_u32 s4, s1, s0
	v_readlane_b32 s0, v253, 2
	s_addc_u32 s5, s0, 0
	s_lshl_b32 s0, s12, 5
	s_ashr_i32 s1, s0, 31
	s_lshl_b64 s[0:1], s[0:1], 9
	s_add_u32 s0, s4, s0
	s_addc_u32 s1, s5, s1
	v_and_b32_e32 v72, 48, v70
	v_mov_b32_e32 v73, v195
	v_lshlrev_b32_e32 v4, 9, v149
	v_lshl_add_u64 v[2:3], s[0:1], 0, v[72:73]
	v_and_b32_e32 v194, 0x1e00, v4
	v_lshl_add_u64 v[4:5], v[2:3], 0, v[194:195]
	v_or_b32_e32 v194, 0x2000, v194
	v_lshl_add_u64 v[6:7], v[2:3], 0, v[194:195]
	global_load_dwordx4 v[58:61], v[4:5], off
	global_load_dwordx4 v[50:53], v[4:5], off offset:64
	global_load_dwordx4 v[62:65], v[6:7], off
	global_load_dwordx4 v[54:57], v[6:7], off offset:64
	global_load_dwordx4 v[42:45], v[4:5], off offset:128
	global_load_dwordx4 v[34:37], v[4:5], off offset:192
	global_load_dwordx4 v[46:49], v[6:7], off offset:128
	global_load_dwordx4 v[38:41], v[6:7], off offset:192
	global_load_dwordx4 v[26:29], v[4:5], off offset:256
	global_load_dwordx4 v[18:21], v[4:5], off offset:320
	global_load_dwordx4 v[30:33], v[6:7], off offset:256
	global_load_dwordx4 v[22:25], v[6:7], off offset:320
	global_load_dwordx4 v[10:13], v[4:5], off offset:384
	s_nop 0
	global_load_dwordx4 v[2:5], v[4:5], off offset:448
	s_nop 0
	global_load_dwordx4 v[14:17], v[6:7], off offset:384
	s_nop 0
	global_load_dwordx4 v[6:9], v[6:7], off offset:448
	s_movk_i32 s0, 0x800
	v_cmp_gt_i32_e32 vcc, s0, v70
	s_barrier
	s_and_saveexec_b64 s[0:1], vcc
	s_cbranch_execz .LBB0_1306
	s_lshl_b32 s6, s14, 4
	v_readlane_b32 s16, v250, 58
	v_and_b32_e32 v67, 1, v70
	v_readlane_b32 s17, v250, 59
	s_lshl_b32 s16, s6, 1
	v_lshlrev_b32_e32 v66, 3, v67
	v_writelane_b32 v250, s16, 58
	v_lshlrev_b32_e32 v71, 4, v67
	v_writelane_b32 v250, s17, 59
	v_lshlrev_b32_e32 v194, 1, v66
	v_ashrrev_i32_e32 v75, 5, v70
	v_bfe_u32 v74, v70, 1, 4
	v_add_u32_e32 v76, s15, v75
	v_lshl_or_b32 v68, v76, 4, v74
	v_mov_b64_e32 v[66:67], s[90:91]
	v_mad_i64_i32 v[66:67], s[6:7], v68, s25, v[66:67]
	v_lshl_add_u64 v[66:67], v[66:67], 0, s[16:17]
	v_lshl_add_u64 v[66:67], v[66:67], 0, v[194:195]
	v_add_co_u32_e32 v66, vcc, 0x39600000, v66
	s_nop 1
	v_addc_co_u32_e32 v67, vcc, 0, v67, vcc
	s_mov_b64 s[6:7], 0x160000
	global_load_dwordx4 v[78:81], v[66:67], off offset:512
	v_lshl_add_u64 v[66:67], v[66:67], 0, s[6:7]
	global_load_dwordx4 v[82:85], v[66:67], off offset:512
	v_lshl_add_u64 v[66:67], v[66:67], 0, s[6:7]
	global_load_dwordx4 v[86:89], v[66:67], off offset:512
	v_lshl_add_u64 v[66:67], v[66:67], 0, s[6:7]
	global_load_dwordx4 v[90:93], v[66:67], off offset:512
	s_movk_i32 s6, 0x210
	v_mul_lo_u32 v75, v75, s6
	v_lshlrev_b32_e32 v74, 5, v74
	v_add3_u32 v74, v75, v74, v71
	s_waitcnt vmcnt(3)
	v_cmp_gt_i32_e32 vcc, 0x220, v76
	s_nop 1
	v_cndmask_b32_e32 v78, 0, v78, vcc
	v_cndmask_b32_e32 v79, 0, v79, vcc
	v_cndmask_b32_e32 v80, 0, v80, vcc
	v_cndmask_b32_e32 v81, 0, v81, vcc
	ds_write_b128 v74, v[78:81]
	s_waitcnt vmcnt(2)
	v_cmp_gt_i32_e32 vcc, 0x210, v76
	s_nop 1
	v_cndmask_b32_e32 v82, 0, v82, vcc
	v_cndmask_b32_e32 v83, 0, v83, vcc
	v_cndmask_b32_e32 v84, 0, v84, vcc
	v_cndmask_b32_e32 v85, 0, v85, vcc
	ds_write_b128 v74, v[82:85] offset:8448
	s_waitcnt vmcnt(1)
	v_cmp_gt_i32_e32 vcc, 0x200, v76
	s_nop 1
	v_cndmask_b32_e32 v86, 0, v86, vcc
	v_cndmask_b32_e32 v87, 0, v87, vcc
	v_cndmask_b32_e32 v88, 0, v88, vcc
	v_cndmask_b32_e32 v89, 0, v89, vcc
	ds_write_b128 v74, v[86:89] offset:16896
	s_waitcnt vmcnt(0)
	v_cmp_gt_i32_e32 vcc, 0x1f0, v76
	s_nop 1
	v_cndmask_b32_e32 v90, 0, v90, vcc
	v_cndmask_b32_e32 v91, 0, v91, vcc
	v_cndmask_b32_e32 v92, 0, v92, vcc
	v_cndmask_b32_e32 v93, 0, v93, vcc
	ds_write_b128 v74, v[90:93] offset:25344
	s_branch .LBB0_1306

; #define LAS __attribute__((address_space(3)))
; template <int K, int MT> __device__ __forceinline__ void wave_mma_batch(const LAS unsigned char* a_lds, int lda, int kb, const bf16x8v (&bfr)[8][2], f32x4 (&acc)[MT][2], int lane) {
;     const int fr = lane & 15, fq = lane >> 4;
; #pragma unroll
;     for (int ks = 0; ks < 8; ++ks)
; #pragma unroll
;         for (int m = 0; m < MT; ++m) { const bf16x8v af = *(const LAS bf16x8v*)(a_lds + (m * 16 + fr) * lda + (kb * 256 + ks * 32 + 8 * fq) * 2);
; #pragma unroll
;             for (int n = 0; n < 2; ++n) acc[m][n] = __builtin_amdgcn_mfma_f32_16x16x32_bf16(bfr[ks][n], af, acc[m][n], 0, 0, 0); }
; }
; __device__ __forceinline__ void ssm_sgemm_item(Frame& F, const Args& AR, int l, int item) {
;     ...
;     __syncthreads();
;     f32x4 acc[MT][2];
; #pragma unroll
;     for (int m = 0; m < MT; ++m)
; #pragma unroll
;         for (int n = 0; n < 2; ++n) acc[m][n] = (f32x4){0.f, 0.f, 0.f, 0.f};
;     wave_mma_batch<K, MT>(at, LDA, 0, b0, acc, F.lane);
.LBB0_1306:
	s_or_b64 exec, exec, s[0:1]
	v_and_b32_e32 v66, 15, v70
	v_mul_u32_u24_e32 v67, 0x210, v66
	v_add3_u32 v67, 0, v72, v67
	s_waitcnt vmcnt(0) lgkmcnt(0)
	s_barrier
	ds_read_b128 v[74:77], v67
	ds_read_b128 v[82:85], v67 offset:8448
	ds_read_b128 v[90:93], v67 offset:16896
	ds_read_b128 v[98:101], v67 offset:25344
	s_waitcnt lgkmcnt(3)
	v_mfma_f32_16x16x32_bf16 v[78:81], v[58:61], v[74:77], 0
	s_lshl_b32 s0, s12, 7
	s_add_i32 s0, s0, 0
	s_bfe_u32 s5, s11, 0x10006
	v_mfma_f32_16x16x32_bf16 v[74:77], v[62:65], v[74:77], 0
	v_readlane_b32 s18, v254, 45
	s_ashr_i32 s16, s11, 7
	s_bfe_i32 s6, s11, 0x10006
	s_waitcnt lgkmcnt(2)
	v_mfma_f32_16x16x32_bf16 v[86:89], v[58:61], v[82:85], 0
	s_sub_i32 s4, 3, s16
	v_readlane_b32 s1, v253, 3
	v_readlane_b32 s19, v254, 46
	v_mfma_f32_16x16x32_bf16 v[82:85], v[62:65], v[82:85], 0
	v_lshlrev_b32_e32 v194, 2, v149
	s_waitcnt lgkmcnt(1)
	v_mfma_f32_16x16x32_bf16 v[94:97], v[58:61], v[90:93], 0
	v_mfma_f32_16x16x32_bf16 v[90:93], v[62:65], v[90:93], 0
	s_waitcnt lgkmcnt(0)
	v_mfma_f32_16x16x32_bf16 v[58:61], v[58:61], v[98:101], 0
	v_mfma_f32_16x16x32_bf16 v[62:65], v[62:65], v[98:101], 0
	ds_read_b128 v[98:101], v67 offset:64
	s_waitcnt lgkmcnt(0)
	v_mfma_f32_16x16x32_bf16 v[78:81], v[50:53], v[98:101], v[78:81]
	v_mfma_f32_16x16x32_bf16 v[74:77], v[54:57], v[98:101], v[74:77]
	ds_read_b128 v[98:101], v67 offset:8512
	s_waitcnt lgkmcnt(0)
	v_mfma_f32_16x16x32_bf16 v[86:89], v[50:53], v[98:101], v[86:89]
	v_mfma_f32_16x16x32_bf16 v[82:85], v[54:57], v[98:101], v[82:85]
	ds_read_b128 v[98:101], v67 offset:16960
	s_waitcnt lgkmcnt(0)
	v_mfma_f32_16x16x32_bf16 v[94:97], v[50:53], v[98:101], v[94:97]
	v_mfma_f32_16x16x32_bf16 v[90:93], v[54:57], v[98:101], v[90:93]
	ds_read_b128 v[98:101], v67 offset:25408
	s_waitcnt lgkmcnt(0)
	v_mfma_f32_16x16x32_bf16 v[50:53], v[50:53], v[98:101], v[58:61]
	s_nop 2
	ds_read_b128 v[58:61], v67 offset:128
	v_mfma_f32_16x16x32_bf16 v[54:57], v[54:57], v[98:101], v[62:65]
	s_waitcnt lgkmcnt(0)
	v_mfma_f32_16x16x32_bf16 v[62:65], v[42:45], v[58:61], v[78:81]
	v_mfma_f32_16x16x32_bf16 v[58:61], v[46:49], v[58:61], v[74:77]
	s_nop 2
	ds_read_b128 v[74:77], v67 offset:8576
	s_waitcnt lgkmcnt(0)
	v_mfma_f32_16x16x32_bf16 v[78:81], v[42:45], v[74:77], v[86:89]
	v_mfma_f32_16x16x32_bf16 v[74:77], v[46:49], v[74:77], v[82:85]
	s_nop 2
	ds_read_b128 v[82:85], v67 offset:17024
	s_waitcnt lgkmcnt(0)
	v_mfma_f32_16x16x32_bf16 v[86:89], v[42:45], v[82:85], v[94:97]
	v_mfma_f32_16x16x32_bf16 v[82:85], v[46:49], v[82:85], v[90:93]
	s_nop 2
	ds_read_b128 v[90:93], v67 offset:25472
	s_waitcnt lgkmcnt(0)
	v_mfma_f32_16x16x32_bf16 v[42:45], v[42:45], v[90:93], v[50:53]
	s_nop 2
	ds_read_b128 v[50:53], v67 offset:192
	v_mfma_f32_16x16x32_bf16 v[46:49], v[46:49], v[90:93], v[54:57]
	s_waitcnt lgkmcnt(0)
	v_mfma_f32_16x16x32_bf16 v[54:57], v[34:37], v[50:53], v[62:65]
	v_mfma_f32_16x16x32_bf16 v[50:53], v[38:41], v[50:53], v[58:61]
	s_nop 2
	ds_read_b128 v[58:61], v67 offset:8640
	s_waitcnt lgkmcnt(0)
	v_mfma_f32_16x16x32_bf16 v[62:65], v[34:37], v[58:61], v[78:81]
	v_mfma_f32_16x16x32_bf16 v[58:61], v[38:41], v[58:61], v[74:77]
	s_nop 2
	ds_read_b128 v[74:77], v67 offset:17088
	s_waitcnt lgkmcnt(0)
	v_mfma_f32_16x16x32_bf16 v[78:81], v[34:37], v[74:77], v[86:89]
	v_mfma_f32_16x16x32_bf16 v[74:77], v[38:41], v[74:77], v[82:85]
	s_nop 2
	ds_read_b128 v[82:85], v67 offset:25536
	s_waitcnt lgkmcnt(0)
	v_mfma_f32_16x16x32_bf16 v[34:37], v[34:37], v[82:85], v[42:45]
	s_nop 2
	ds_read_b128 v[42:45], v67 offset:256
	v_mfma_f32_16x16x32_bf16 v[38:41], v[38:41], v[82:85], v[46:49]
	s_waitcnt lgkmcnt(0)
	v_mfma_f32_16x16x32_bf16 v[46:49], v[26:29], v[42:45], v[54:57]
	v_mfma_f32_16x16x32_bf16 v[42:45], v[30:33], v[42:45], v[50:53]
	s_nop 2
	ds_read_b128 v[50:53], v67 offset:8704
	s_waitcnt lgkmcnt(0)
	v_mfma_f32_16x16x32_bf16 v[54:57], v[26:29], v[50:53], v[62:65]
	v_mfma_f32_16x16x32_bf16 v[50:53], v[30:33], v[50:53], v[58:61]
	s_nop 2
	ds_read_b128 v[58:61], v67 offset:17152
	s_waitcnt lgkmcnt(0)
	v_mfma_f32_16x16x32_bf16 v[62:65], v[26:29], v[58:61], v[78:81]
	v_mfma_f32_16x16x32_bf16 v[58:61], v[30:33], v[58:61], v[74:77]
	s_nop 2
	ds_read_b128 v[74:77], v67 offset:25600
	s_waitcnt lgkmcnt(0)
	v_mfma_f32_16x16x32_bf16 v[26:29], v[26:29], v[74:77], v[34:37]
	s_nop 2
	ds_read_b128 v[34:37], v67 offset:320
	v_mfma_f32_16x16x32_bf16 v[30:33], v[30:33], v[74:77], v[38:41]
	s_waitcnt lgkmcnt(0)
	v_mfma_f32_16x16x32_bf16 v[38:41], v[18:21], v[34:37], v[46:49]
	v_mfma_f32_16x16x32_bf16 v[34:37], v[22:25], v[34:37], v[42:45]
	s_nop 2
	ds_read_b128 v[42:45], v67 offset:8768
	s_waitcnt lgkmcnt(0)
	v_mfma_f32_16x16x32_bf16 v[46:49], v[18:21], v[42:45], v[54:57]
	v_mfma_f32_16x16x32_bf16 v[42:45], v[22:25], v[42:45], v[50:53]
	s_nop 2
	ds_read_b128 v[50:53], v67 offset:17216
	s_waitcnt lgkmcnt(0)
	v_mfma_f32_16x16x32_bf16 v[54:57], v[18:21], v[50:53], v[62:65]
	v_mfma_f32_16x16x32_bf16 v[50:53], v[22:25], v[50:53], v[58:61]
	s_nop 2
	ds_read_b128 v[58:61], v67 offset:25664
	s_waitcnt lgkmcnt(0)
	v_mfma_f32_16x16x32_bf16 v[18:21], v[18:21], v[58:61], v[26:29]
	s_nop 2
	ds_read_b128 v[26:29], v67 offset:384
	v_mfma_f32_16x16x32_bf16 v[22:25], v[22:25], v[58:61], v[30:33]
	s_waitcnt lgkmcnt(0)
	v_mfma_f32_16x16x32_bf16 v[30:33], v[10:13], v[26:29], v[38:41]
	v_mfma_f32_16x16x32_bf16 v[26:29], v[14:17], v[26:29], v[34:37]
	s_nop 2
	ds_read_b128 v[34:37], v67 offset:8832
	s_waitcnt lgkmcnt(0)
	v_mfma_f32_16x16x32_bf16 v[38:41], v[10:13], v[34:37], v[46:49]
	v_mfma_f32_16x16x32_bf16 v[34:37], v[14:17], v[34:37], v[42:45]
	s_nop 2
	ds_read_b128 v[42:45], v67 offset:17280
	s_waitcnt lgkmcnt(0)
; #define LAS __attribute__((address_space(3)))
; __device__ __forceinline__ void ssm_sgemm_item(Frame& F, const Args& AR, int l, int item) {
;     ...
;     { const int fr = F.lane & 15, fq = F.lane >> 4;
; #pragma unroll
;       for (int m = 0; m < MT; ++m)
; #pragma unroll
;         for (int n = 0; n < 2; ++n) *(LAS f32x4*)(sl + (m * 16 + fr) * SLD + F.wave * 32 + n * 16 + 4 * fq) = acc[m][n]; }
;     __syncthreads();
;     const int dir = F.wave & 1, cpos = F.wave >> 1, sub = dir ? 3 - cpos : cpos, p = F.lane;
;     const f32x2 a = *(const f32x2*)((const float*)(F.ws + WS_A16) + ((size_t)((l * 2 + dir) * 32 + g) * 64 + p) * 2);
;     float sr[16], si[16];
; #pragma unroll
;     for (int i = 0; i < 16; ++i) { const int row = sub * 16 + (dir ? 15 - i : i); sr[i] = sl[row * SLD + dir * 128 + p]; si[i] = sl[row * SLD + dir * 128 + 64 + p]; }
;     float hr = 0.f, hi = 0.f;
; #pragma unroll
;     for (int i = 0; i < 16; ++i) { const float nr = a.x * hr - a.y * hi + sr[i], ni = a.x * hi + a.y * hr + si[i]; hr = nr; hi = ni; }
	v_mfma_f32_16x16x32_bf16 v[46:49], v[10:13], v[42:45], v[54:57]
	v_mfma_f32_16x16x32_bf16 v[42:45], v[14:17], v[42:45], v[50:53]
	s_nop 2
	ds_read_b128 v[50:53], v67 offset:25728
	s_waitcnt lgkmcnt(0)
	v_mfma_f32_16x16x32_bf16 v[10:13], v[10:13], v[50:53], v[18:21]
	s_nop 2
	ds_read_b128 v[18:21], v67 offset:448
	v_mfma_f32_16x16x32_bf16 v[14:17], v[14:17], v[50:53], v[22:25]
	s_waitcnt lgkmcnt(0)
	v_mfma_f32_16x16x32_bf16 v[22:25], v[2:5], v[18:21], v[30:33]
	v_mfma_f32_16x16x32_bf16 v[18:21], v[6:9], v[18:21], v[26:29]
	s_nop 2
	ds_read_b128 v[26:29], v67 offset:8896
	s_waitcnt lgkmcnt(0)
	v_mfma_f32_16x16x32_bf16 v[30:33], v[2:5], v[26:29], v[38:41]
	v_mfma_f32_16x16x32_bf16 v[26:29], v[6:9], v[26:29], v[34:37]
	s_nop 2
	ds_read_b128 v[34:37], v67 offset:17344
	s_waitcnt lgkmcnt(0)
	v_mfma_f32_16x16x32_bf16 v[38:41], v[2:5], v[34:37], v[46:49]
	v_mfma_f32_16x16x32_bf16 v[34:37], v[6:9], v[34:37], v[42:45]
	s_nop 2
	ds_read_b128 v[42:45], v67 offset:25792
	s_waitcnt lgkmcnt(0)
	v_mfma_f32_16x16x32_bf16 v[2:5], v[2:5], v[42:45], v[10:13]
	s_nop 2
	v_mul_u32_u24_e32 v10, 0x410, v66
	v_add3_u32 v10, s0, v10, v72
	s_lshl_b32 s0, s5, 5
	s_or_b32 s0, s0, s18
	s_or_b32 s0, s0, s14
	s_lshl_b32 s0, s0, 9
	s_add_u32 s0, s1, s0
	v_readlane_b32 s1, v253, 4
	v_mfma_f32_16x16x32_bf16 v[6:9], v[6:9], v[42:45], v[14:17]
	v_add_u32_e32 v11, 0x9000, v10
	ds_write_b128 v10, v[22:25] offset:36864
	ds_write_b128 v10, v[18:21] offset:36928
	ds_write_b128 v10, v[30:33] offset:53504
	ds_write_b128 v10, v[26:29] offset:53568
	ds_write_b128 v11, v[38:41] offset:33280
	ds_write_b128 v11, v[34:37] offset:33344
	ds_write_b128 v11, v[2:5] offset:49920
	ds_write_b128 v11, v[6:9] offset:49984
	s_addc_u32 s1, s1, 0
	v_lshlrev_b32_e32 v37, 3, v149
	s_waitcnt lgkmcnt(0)
	s_barrier
	global_load_dwordx2 v[2:3], v37, s[0:1]
	s_cmp_eq_u32 s5, 0
	s_cselect_b32 s4, s16, s4
	s_cselect_b32 s31, 1, 14
	s_cselect_b32 s30, 2, 13
	s_cselect_b32 s29, 3, 12
	s_cselect_b32 s28, 4, 11
	s_cselect_b32 s25, 5, 10
	s_cselect_b32 s24, 6, 9
	s_cselect_b32 s23, 9, 6
	s_cselect_b32 s22, 10, 5
	s_cselect_b32 s21, 11, 4
	s_cselect_b32 s20, 12, 3
	s_cselect_b32 s19, 13, 2
	s_cselect_b32 s18, 14, 1
	s_cselect_b32 s17, 15, 0
	s_lshl_b32 s35, s4, 4
	s_and_b32 s34, s6, 15
	s_lshl_b32 s36, s5, 9
	s_or_b32 s0, s35, s34
	s_add_i32 s9, s36, 0
	s_mulk_i32 s0, 0x410
	s_add_i32 s0, s9, s0
	v_add_u32_e32 v4, s0, v194
	ds_read2st64_b32 v[34:35], v4 offset0:144 offset1:145
	s_or_b32 s0, s35, s31
	s_mulk_i32 s0, 0x410
	s_add_i32 s0, s9, s0
	v_add_u32_e32 v4, s0, v194
	s_or_b32 s0, s35, s30
	ds_read2st64_b32 v[32:33], v4 offset0:144 offset1:145
	s_mulk_i32 s0, 0x410
	s_add_i32 s0, s9, s0
	v_add_u32_e32 v4, s0, v194
	ds_read2st64_b32 v[30:31], v4 offset0:144 offset1:145
	s_or_b32 s0, s35, s29
	s_mulk_i32 s0, 0x410
	s_add_i32 s0, s9, s0
	v_add_u32_e32 v4, s0, v194
	s_or_b32 s0, s35, s28
	ds_read2st64_b32 v[28:29], v4 offset0:144 offset1:145
	s_mulk_i32 s0, 0x410
	s_add_i32 s0, s9, s0
	v_add_u32_e32 v4, s0, v194
	ds_read2st64_b32 v[26:27], v4 offset0:144 offset1:145
	s_or_b32 s0, s35, s25
	s_mulk_i32 s0, 0x410
	s_add_i32 s0, s9, s0
	v_add_u32_e32 v4, s0, v194
	s_or_b32 s0, s35, s24
	ds_read2st64_b32 v[24:25], v4 offset0:144 offset1:145
	s_mulk_i32 s0, 0x410
	s_add_i32 s0, s9, s0
	v_add_u32_e32 v4, s0, v194
	s_add_i32 s27, s5, 7
	ds_read2st64_b32 v[22:23], v4 offset0:144 offset1:145
	s_or_b32 s0, s35, s27
	s_mulk_i32 s0, 0x410
	s_add_i32 s0, s9, s0
	s_sub_i32 s26, 8, s5
	v_add_u32_e32 v4, s0, v194
	s_or_b32 s0, s35, s26
	ds_read2st64_b32 v[20:21], v4 offset0:144 offset1:145
	s_mulk_i32 s0, 0x410
	s_add_i32 s0, s9, s0
	v_add_u32_e32 v4, s0, v194
	ds_read2st64_b32 v[18:19], v4 offset0:144 offset1:145
	s_or_b32 s0, s35, s23
	s_mulk_i32 s0, 0x410
	s_add_i32 s0, s9, s0
	v_add_u32_e32 v4, s0, v194
	s_or_b32 s0, s35, s22
	ds_read2st64_b32 v[16:17], v4 offset0:144 offset1:145
	s_mulk_i32 s0, 0x410
	s_add_i32 s0, s9, s0
	v_add_u32_e32 v4, s0, v194
	ds_read2st64_b32 v[14:15], v4 offset0:144 offset1:145
	s_or_b32 s0, s35, s21
	s_mulk_i32 s0, 0x410
	s_add_i32 s0, s9, s0
	s_waitcnt vmcnt(0)
	v_pk_mul_f32 v[38:39], v[2:3], 0 op_sel_hi:[1,0]
	v_add_u32_e32 v4, s0, v194
	v_sub_f32_e32 v36, v38, v39
	v_add_f32_e32 v38, v38, v39
	s_waitcnt lgkmcnt(10)
	v_add_f32_e32 v38, v35, v38
	v_add_f32_e32 v36, v34, v36
	v_pk_mul_f32 v[38:39], v[2:3], v[38:39] op_sel:[1,0] op_sel_hi:[0,0]
	v_pk_fma_f32 v[40:41], v[2:3], v[36:37], v[38:39] neg_lo:[0,0,1] neg_hi:[0,0,1]
	v_pk_fma_f32 v[38:39], v[2:3], v[36:37], v[38:39] op_sel_hi:[1,0,1]
	s_or_b32 s0, s35, s20
	v_mov_b32_e32 v41, v39
	s_waitcnt lgkmcnt(9)
	v_pk_add_f32 v[38:39], v[32:33], v[40:41]
	ds_read2st64_b32 v[12:13], v4 offset0:144 offset1:145
	v_pk_mul_f32 v[40:41], v[2:3], v[38:39]
	v_pk_mul_f32 v[38:39], v[2:3], v[38:39] op_sel:[0,1] op_sel_hi:[1,0]
	v_sub_f32_e32 v36, v40, v41
	v_add_f32_e32 v38, v38, v39
	s_waitcnt lgkmcnt(9)
	v_add_f32_e32 v38, v31, v38
	v_add_f32_e32 v36, v30, v36
	v_pk_mul_f32 v[38:39], v[2:3], v[38:39] op_sel:[1,0] op_sel_hi:[0,0]
	v_pk_fma_f32 v[40:41], v[2:3], v[36:37], v[38:39] neg_lo:[0,0,1] neg_hi:[0,0,1]
	v_pk_fma_f32 v[38:39], v[2:3], v[36:37], v[38:39] op_sel_hi:[1,0,1]
	s_mulk_i32 s0, 0x410
	v_mov_b32_e32 v41, v39
	s_waitcnt lgkmcnt(8)
; __device__ __forceinline__ void ssm_sgemm_item(Frame& F, const Args& AR, int l, int item) {
;     ...
; #pragma unroll
;     for (int i = 0; i < 16; ++i) { const float nr = a.x * hr - a.y * hi + sr[i], ni = a.x * hi + a.y * hr + si[i]; hr = nr; hi = ni; }
;     ex[(F.wave * 64 + p) * 2] = hr; ex[(F.wave * 64 + p) * 2 + 1] = hi;
;     float pr = a.x, pi = a.y;
; #pragma unroll
;     for (int i = 0; i < 4; ++i) { const float nr = pr * pr - pi * pi, ni = 2.0f * pr * pi; pr = nr; pi = ni; }
;     __syncthreads();
;     hr = 0.f; hi = 0.f;
;     if (rt < 8) for (int c = 0; c < cpos; ++c) { const int ww = (c << 1) | dir; const float er = ex[(ww * 64 + p) * 2], ei = ex[(ww * 64 + p) * 2 + 1];
;         const float nr = pr * hr - pi * hi + er, ni = pr * hi + pi * hr + ei; hr = nr; hi = ni; }
	v_pk_add_f32 v[38:39], v[28:29], v[40:41]
	s_add_i32 s0, s9, s0
	v_pk_mul_f32 v[40:41], v[2:3], v[38:39]
	v_pk_mul_f32 v[38:39], v[2:3], v[38:39] op_sel:[0,1] op_sel_hi:[1,0]
	v_sub_f32_e32 v36, v40, v41
	v_add_f32_e32 v38, v38, v39
	s_waitcnt lgkmcnt(7)
	v_add_f32_e32 v38, v27, v38
	v_add_f32_e32 v36, v26, v36
	v_pk_mul_f32 v[38:39], v[2:3], v[38:39] op_sel:[1,0] op_sel_hi:[0,0]
	v_pk_fma_f32 v[40:41], v[2:3], v[36:37], v[38:39] neg_lo:[0,0,1] neg_hi:[0,0,1]
	v_pk_fma_f32 v[38:39], v[2:3], v[36:37], v[38:39] op_sel_hi:[1,0,1]
	v_add_u32_e32 v4, s0, v194
	v_mov_b32_e32 v41, v39
	s_waitcnt lgkmcnt(6)
	v_pk_add_f32 v[38:39], v[24:25], v[40:41]
	ds_read2st64_b32 v[10:11], v4 offset0:144 offset1:145
	v_pk_mul_f32 v[40:41], v[2:3], v[38:39]
	v_pk_mul_f32 v[38:39], v[2:3], v[38:39] op_sel:[0,1] op_sel_hi:[1,0]
	v_sub_f32_e32 v36, v40, v41
	v_add_f32_e32 v38, v38, v39
	s_waitcnt lgkmcnt(6)
	v_add_f32_e32 v38, v23, v38
	v_add_f32_e32 v36, v22, v36
	v_pk_mul_f32 v[38:39], v[2:3], v[38:39] op_sel:[1,0] op_sel_hi:[0,0]
	v_pk_fma_f32 v[40:41], v[2:3], v[36:37], v[38:39] neg_lo:[0,0,1] neg_hi:[0,0,1]
	v_pk_fma_f32 v[38:39], v[2:3], v[36:37], v[38:39] op_sel_hi:[1,0,1]
	s_or_b32 s0, s35, s19
	v_mov_b32_e32 v41, v39
	s_waitcnt lgkmcnt(5)
	v_pk_add_f32 v[38:39], v[20:21], v[40:41]
	s_mulk_i32 s0, 0x410
	v_pk_mul_f32 v[40:41], v[2:3], v[38:39]
	v_pk_mul_f32 v[38:39], v[2:3], v[38:39] op_sel:[0,1] op_sel_hi:[1,0]
	v_sub_f32_e32 v36, v40, v41
	v_add_f32_e32 v38, v38, v39
	s_waitcnt lgkmcnt(4)
	v_add_f32_e32 v38, v19, v38
	v_add_f32_e32 v36, v18, v36
	v_pk_mul_f32 v[38:39], v[2:3], v[38:39] op_sel:[1,0] op_sel_hi:[0,0]
	v_pk_fma_f32 v[40:41], v[2:3], v[36:37], v[38:39] neg_lo:[0,0,1] neg_hi:[0,0,1]
	v_pk_fma_f32 v[38:39], v[2:3], v[36:37], v[38:39] op_sel_hi:[1,0,1]
	s_add_i32 s0, s9, s0
	v_mov_b32_e32 v41, v39
	s_waitcnt lgkmcnt(3)
	v_pk_add_f32 v[38:39], v[16:17], v[40:41]
	v_add_u32_e32 v4, s0, v194
	v_pk_mul_f32 v[40:41], v[2:3], v[38:39]
	v_pk_mul_f32 v[38:39], v[2:3], v[38:39] op_sel:[0,1] op_sel_hi:[1,0]
	v_sub_f32_e32 v36, v40, v41
	v_add_f32_e32 v38, v38, v39
	s_waitcnt lgkmcnt(2)
	v_add_f32_e32 v38, v15, v38
	v_add_f32_e32 v36, v14, v36
	v_pk_mul_f32 v[38:39], v[2:3], v[38:39] op_sel:[1,0] op_sel_hi:[0,0]
	v_pk_fma_f32 v[40:41], v[2:3], v[36:37], v[38:39] neg_lo:[0,0,1] neg_hi:[0,0,1]
	v_pk_fma_f32 v[38:39], v[2:3], v[36:37], v[38:39] op_sel_hi:[1,0,1]
	s_or_b32 s0, s35, s18
	v_mov_b32_e32 v41, v39
	s_waitcnt lgkmcnt(1)
	v_pk_add_f32 v[38:39], v[12:13], v[40:41]
	ds_read2st64_b32 v[8:9], v4 offset0:144 offset1:145
	v_pk_mul_f32 v[40:41], v[2:3], v[38:39]
	v_pk_mul_f32 v[38:39], v[2:3], v[38:39] op_sel:[0,1] op_sel_hi:[1,0]
	s_mulk_i32 s0, 0x410
	v_add_f32_e32 v38, v38, v39
	s_add_i32 s0, s9, s0
	v_sub_f32_e32 v36, v40, v41
	s_waitcnt lgkmcnt(1)
	v_add_f32_e32 v38, v11, v38
	v_add_u32_e32 v4, s0, v194
	v_add_f32_e32 v36, v10, v36
	v_pk_mul_f32 v[38:39], v[2:3], v[38:39] op_sel:[1,0] op_sel_hi:[0,0]
	ds_read2st64_b32 v[6:7], v4 offset0:144 offset1:145
	s_or_b32 s0, s35, s17
	v_pk_fma_f32 v[40:41], v[2:3], v[36:37], v[38:39] neg_lo:[0,0,1] neg_hi:[0,0,1]
	v_pk_fma_f32 v[38:39], v[2:3], v[36:37], v[38:39] op_sel_hi:[1,0,1]
	s_mulk_i32 s0, 0x410
	v_mov_b32_e32 v41, v39
	s_add_i32 s0, s9, s0
	s_waitcnt lgkmcnt(1)
	v_pk_add_f32 v[38:39], v[8:9], v[40:41]
	v_add_u32_e32 v4, s0, v194
	v_pk_mul_f32 v[40:41], v[2:3], v[38:39]
	v_pk_mul_f32 v[38:39], v[2:3], v[38:39] op_sel:[0,1] op_sel_hi:[1,0]
	s_lshl_b32 s0, s12, 9
	ds_read2st64_b32 v[4:5], v4 offset0:144 offset1:145
	v_add_f32_e32 v38, v38, v39
	s_add_i32 s0, s0, 0
	v_sub_f32_e32 v36, v40, v41
	s_waitcnt lgkmcnt(1)
	v_add_f32_e32 v38, v7, v38
	v_add_u32_e32 v39, s0, v37
	v_add_f32_e32 v36, v6, v36
	v_add_u32_e32 v42, 0x19800, v39
	v_pk_mul_f32 v[38:39], v[2:3], v[38:39] op_sel:[1,0] op_sel_hi:[0,0]
	s_cmpk_lt_u32 s8, 0x100
	v_pk_fma_f32 v[40:41], v[2:3], v[36:37], v[38:39] neg_lo:[0,0,1] neg_hi:[0,0,1]
	v_pk_fma_f32 v[38:39], v[2:3], v[36:37], v[38:39] op_sel_hi:[1,0,1]
	s_cselect_b64 s[0:1], -1, 0
	s_cmpk_gt_u32 s8, 0xff
	v_mov_b32_e32 v41, v39
	s_cselect_b64 s[6:7], -1, 0
	s_cmp_gt_i32 s16, 0
	s_waitcnt lgkmcnt(0)
	v_pk_add_f32 v[38:39], v[4:5], v[40:41]
	s_cselect_b64 s[38:39], -1, 0
	ds_write_b64 v42, v[38:39]
	s_and_b64 s[38:39], s[0:1], s[38:39]
	v_mov_b32_e32 v39, 0
	s_and_b64 vcc, exec, s[38:39]
	v_mov_b32_e32 v38, v39
	s_waitcnt lgkmcnt(0)
	s_barrier
	s_cbranch_vccz .LBB0_1309
	v_pk_mul_f32 v[38:39], v[2:3], v[2:3]
	v_add_f32_e32 v36, v2, v2
	v_sub_f32_e32 v38, v38, v39
	v_mul_f32_e32 v36, v3, v36
	v_add_f32_e32 v39, v38, v38
	v_mul_f32_e32 v38, v38, v38
	v_mul_f32_e32 v39, v36, v39
	v_fma_f32 v36, -v36, v36, v38
	v_add_f32_e32 v38, v36, v36
	v_mul_f32_e32 v38, v39, v38
	v_mul_f32_e32 v39, v39, v39
	v_fma_f32 v39, v36, v36, -v39
	v_add_f32_e32 v36, v39, v39
	v_mul_f32_e32 v36, v38, v36
	v_mul_f32_e32 v38, v38, v38
	v_fma_f32 v40, v39, v39, -v38
	s_add_i32 s9, s9, 0x19800
	v_mov_b32_e32 v38, 0
	v_add_u32_e32 v42, s9, v37
	v_mov_b32_e32 v41, v40
	v_mov_b32_e32 v37, v36
	s_mov_b32 s8, s16
	v_mov_b32_e32 v39, v38

; template <int PH, int MT> __device__ __forceinline__ void ssm_gemm_rows(Frame& F, const Args& AR, int l, int g, int row0) {
;     ...
;     if (F.tid < 128) { const int dir = F.tid >> 6, p = F.tid & 63, t = row0 >> 6, b = t >> 2, i = t & 3;
;         const float* ET = (const float*)(F.ws + WS_ET) + (size_t)g * 256 + dir * 128 + p;
;         const f32x2 a64 = *(const f32x2*)(POW + ((((size_t)(l * 2 + dir) * 32 + g) * 65 + 64) * 64 + p) * 2);
;         float hr = ET[(size_t)(8 + b) * 8192], hi = ET[(size_t)(8 + b) * 8192 + 64];
;         if (dir == 0) { for (int j = 0; j < i; ++j) { const float er = ET[(size_t)(4 * b + j) * 8192], ei = ET[(size_t)(4 * b + j) * 8192 + 64];
;                 const float nr = a64.x * hr - a64.y * hi + er, ni = a64.x * hi + a64.y * hr + ei; hr = nr; hi = ni; } }
;         else { for (int j = 3; j > i; --j) { const float er = ET[(size_t)(4 * b + j) * 8192], ei = ET[(size_t)(4 * b + j) * 8192 + 64];
;                 const float nr = a64.x * hr - a64.y * hi + er, ni = a64.x * hi + a64.y * hr + ei; hr = nr; hi = ni; } }
;         hs[F.tid * 2] = hr; hs[F.tid * 2 + 1] = hi; }
.LBB0_1597:
	v_readlane_b32 s4, v250, 58
	s_lshl_b32 s0, s16, 18
	v_readlane_b32 s5, v250, 59
	s_mov_b32 s1, s5
	s_or_b32 s0, s0, s10
	v_lshl_add_u64 v[68:69], v[168:169], 0, s[0:1]
	v_mov_b32_e32 v179, v195
	v_mov_b32_e32 v177, v195
	v_lshl_add_u64 v[66:67], v[68:69], 0, v[178:179]
	v_lshl_add_u64 v[6:7], v[68:69], 0, v[176:177]
	global_load_dwordx4 v[58:61], v[66:67], off
	global_load_dwordx4 v[50:53], v[66:67], off offset:64
	global_load_dwordx4 v[62:65], v[6:7], off
	global_load_dwordx4 v[54:57], v[6:7], off offset:64
	global_load_dwordx4 v[42:45], v[66:67], off offset:128
	global_load_dwordx4 v[34:37], v[66:67], off offset:192
	global_load_dwordx4 v[46:49], v[6:7], off offset:128
	global_load_dwordx4 v[38:41], v[6:7], off offset:192
	global_load_dwordx4 v[26:29], v[66:67], off offset:256
	global_load_dwordx4 v[18:21], v[66:67], off offset:320
	global_load_dwordx4 v[30:33], v[6:7], off offset:256
	global_load_dwordx4 v[22:25], v[6:7], off offset:320
	global_load_dwordx4 v[10:13], v[66:67], off offset:384
	global_load_dwordx4 v[2:5], v[66:67], off offset:448
	global_load_dwordx4 v[14:17], v[6:7], off offset:384
	s_nop 0
	global_load_dwordx4 v[6:9], v[6:7], off offset:448
	s_mov_b32 s21, s5
	s_barrier
	s_and_saveexec_b64 s[0:1], s[40:41]
	s_cbranch_execz .LBB0_1608
	s_lshl_b32 s6, s16, 10
	s_mov_b32 s7, s21
	v_or_b32_e32 v72, s16, v164
	s_movk_i32 s5, 0x1040
	s_ashr_i32 s4, s15, 7
	v_lshl_add_u64 v[70:71], v[162:163], 0, s[6:7]
	v_mad_u64_u32 v[72:73], s[6:7], v72, s5, v[166:167]
	v_mad_i32_i24 v73, v165, s5, v73
	s_ashr_i32 s5, s4, 31
	s_lshl_b64 s[6:7], s[4:5], 15
	v_lshl_add_u64 v[70:71], v[70:71], 0, s[6:7]
	s_mov_b64 s[6:7], 0x40000
	v_lshl_add_u64 v[72:73], v[72:73], 3, s[34:35]
	v_lshl_add_u64 v[74:75], v[70:71], 0, s[6:7]
	v_add_co_u32_e32 v70, vcc, 0x40000, v70
	s_and_b32 s5, s14, 31
	s_nop 0
	v_addc_co_u32_e32 v71, vcc, 0, v71, vcc
	global_load_dwordx2 v[72:73], v[72:73], off
	s_nop 0
	global_load_dword v70, v[70:71], off
	s_nop 0
	global_load_dword v74, v[74:75], off offset:256
	s_lshl_b32 s20, s5, 10
	s_bfe_u32 s5, s15, 0x20005
	s_and_saveexec_b64 s[6:7], s[44:45]
	s_xor_b64 s[6:7], exec, s[6:7]
	s_cbranch_execz .LBB0_1603
	s_cmp_eq_u32 s5, 3
	s_cbranch_scc1 .LBB0_1602
	s_lshl_b32 s8, s4, 2
	s_ashr_i32 s9, s8, 31
	s_lshl_b64 s[8:9], s[8:9], 15
	s_or_b64 s[8:9], s[8:9], s[20:21]
	v_lshl_add_u64 v[78:79], v[170:171], 0, s[8:9]
	s_movk_i32 s18, 0x8000
	s_mov_b32 s19, -1
	global_load_dword v208, v[78:79], off
	global_load_dword v209, v[78:79], off offset:256
	v_lshl_add_u64 v[78:79], v[78:79], 0, s[18:19]
	global_load_dword v210, v[78:79], off
	global_load_dword v211, v[78:79], off offset:256
	v_lshl_add_u64 v[78:79], v[78:79], 0, s[18:19]
	global_load_dword v212, v[78:79], off
	global_load_dword v213, v[78:79], off offset:256
	s_waitcnt vmcnt(0)
	v_pk_mov_b32 v[76:77], v[72:73], v[72:73] op_sel:[1,0]
	v_pk_mul_f32 v[74:75], v[76:77], v[74:75] op_sel_hi:[1,0]
	v_pk_fma_f32 v[82:83], v[72:73], v[70:71], v[74:75] neg_lo:[0,0,1] neg_hi:[0,0,1]
	v_pk_fma_f32 v[70:71], v[72:73], v[70:71], v[74:75] op_sel_hi:[1,0,1]
	v_mov_b32_e32 v83, v71
	v_pk_add_f32 v[70:71], v[82:83], v[208:209]
	s_nop 0
	v_mov_b32_e32 v74, v71
	s_cmp_lt_u32 s5, 2
	s_cbranch_scc0 .LBB0_1602
	v_pk_mul_f32 v[74:75], v[76:77], v[74:75] op_sel_hi:[1,0]
	v_pk_fma_f32 v[82:83], v[72:73], v[70:71], v[74:75] neg_lo:[0,0,1] neg_hi:[0,0,1]
	v_pk_fma_f32 v[70:71], v[72:73], v[70:71], v[74:75] op_sel_hi:[1,0,1]
	v_mov_b32_e32 v83, v71
	v_pk_add_f32 v[70:71], v[82:83], v[210:211]
	s_nop 0
	v_mov_b32_e32 v74, v71
	s_cmp_lt_u32 s5, 1
	s_cbranch_scc0 .LBB0_1602
	v_pk_mul_f32 v[74:75], v[76:77], v[74:75] op_sel_hi:[1,0]
	v_pk_fma_f32 v[82:83], v[72:73], v[70:71], v[74:75] neg_lo:[0,0,1] neg_hi:[0,0,1]
	v_pk_fma_f32 v[70:71], v[72:73], v[70:71], v[74:75] op_sel_hi:[1,0,1]
	v_mov_b32_e32 v83, v71
	v_pk_add_f32 v[70:71], v[82:83], v[212:213]
	s_nop 0
	v_mov_b32_e32 v74, v71
.LBB0_1602:
.LBB0_1603:
	s_andn2_saveexec_b64 s[6:7], s[6:7]
	s_cbranch_execz .LBB0_1607
	s_cmp_eq_u32 s5, 0
	s_cbranch_scc1 .LBB0_1607
	s_lshl_b32 s8, s4, 2
	s_ashr_i32 s9, s8, 31
	s_lshl_b64 s[8:9], s[8:9], 15
	s_or_b64 s[8:9], s[8:9], s[20:21]
	v_lshl_add_u64 v[78:79], v[172:173], 0, s[8:9]
	s_mov_b64 s[8:9], 0x8000
	global_load_dword v208, v[78:79], off
	global_load_dword v209, v[78:79], off offset:256
	v_lshl_add_u64 v[78:79], v[78:79], 0, s[8:9]
	global_load_dword v210, v[78:79], off
	global_load_dword v211, v[78:79], off offset:256
	v_lshl_add_u64 v[78:79], v[78:79], 0, s[8:9]
	global_load_dword v212, v[78:79], off
	global_load_dword v213, v[78:79], off offset:256
	s_waitcnt vmcnt(0)
	v_pk_mov_b32 v[76:77], v[72:73], v[72:73] op_sel:[1,0]
	v_pk_mul_f32 v[74:75], v[76:77], v[74:75] op_sel_hi:[1,0]
	v_pk_fma_f32 v[82:83], v[72:73], v[70:71], v[74:75] neg_lo:[0,0,1] neg_hi:[0,0,1]
	v_pk_fma_f32 v[70:71], v[72:73], v[70:71], v[74:75] op_sel_hi:[1,0,1]
	v_mov_b32_e32 v83, v71
	v_pk_add_f32 v[70:71], v[82:83], v[208:209]
	s_nop 0
	v_mov_b32_e32 v74, v71
	s_cmp_lt_u32 s5, 2
	s_cbranch_scc1 .LBB0_1607
	v_pk_mul_f32 v[74:75], v[76:77], v[74:75] op_sel_hi:[1,0]
	v_pk_fma_f32 v[82:83], v[72:73], v[70:71], v[74:75] neg_lo:[0,0,1] neg_hi:[0,0,1]
	v_pk_fma_f32 v[70:71], v[72:73], v[70:71], v[74:75] op_sel_hi:[1,0,1]
	v_mov_b32_e32 v83, v71
	v_pk_add_f32 v[70:71], v[82:83], v[210:211]
	s_nop 0
	v_mov_b32_e32 v74, v71
	s_cmp_lt_u32 s5, 3
	s_cbranch_scc1 .LBB0_1607
	v_pk_mul_f32 v[74:75], v[76:77], v[74:75] op_sel_hi:[1,0]
	v_pk_fma_f32 v[82:83], v[72:73], v[70:71], v[74:75] neg_lo:[0,0,1] neg_hi:[0,0,1]
	v_pk_fma_f32 v[70:71], v[72:73], v[70:71], v[74:75] op_sel_hi:[1,0,1]
	v_mov_b32_e32 v83, v71
	v_pk_add_f32 v[70:71], v[82:83], v[212:213]
	s_nop 0
	v_mov_b32_e32 v74, v71
